# stack: P9 two-pass gather + ret_state 2-ahead prefetch + P0 x-conversion fast path
# speedup vs baseline: 1.0011x; 1.0011x over previous
.LBB0_5:
	s_or_b64 exec, exec, s[2:3]
	s_add_u32 s2, s0, 0x298
	s_load_dword s88, s[0:1], 0x298
	s_addc_u32 s3, s1, 0
	s_mov_b32 s89, 0
	v_writelane_b32 v253, s2, 49
	v_mov_b32_e32 v6, v0
	s_mov_b32 s97, s89
	v_writelane_b32 v253, s3, 50
	s_lshl_b64 s[2:3], s[96:97], 9
	v_ashrrev_i32_e32 v7, 31, v6
	v_lshl_add_u64 v[8:9], s[2:3], 0, v[6:7]
	s_mov_b64 s[4:5], 0x208000
	s_waitcnt lgkmcnt(0)
	s_lshl_b64 s[2:3], s[88:89], 9
	v_cmp_gt_u64_e32 vcc, s[4:5], v[8:9]
	v_lshlrev_b32_e32 v1, 3, v6
	s_and_saveexec_b64 s[4:5], vcc
	s_cbranch_execz .LBB0_14
	s_load_dwordx16 s[8:23], s[0:1], 0x100
	v_and_b32_e32 v2, 0x3f8, v1
	v_mov_b32_e32 v11, 0
	v_lshlrev_b32_e32 v10, 1, v2
	s_waitcnt lgkmcnt(0)
	s_mov_b32 s12, 0xff000000
	v_lshl_add_u64 v[12:13], s[20:21], 0, v[10:11]
	s_mov_b64 s[6:7], 0
	s_mov_b64 s[8:9], 0x204000
	s_mov_b64 s[10:11], 0x1fffff
	s_movk_i32 s13, 0x3ff
	v_lshlrev_b32_e32 v10, 2, v2
	s_movk_i32 s20, 0x7fff
	s_mov_b64 s[14:15], 0x207fff
	v_mov_b32_e32 v7, 1
	v_mov_b64_e32 v[14:15], v[8:9]
	s_cmp_lg_u32 s88, 0x100
	s_cbranch_scc1 .LBB0_9
	s_load_dwordx2 s[36:37], s[0:1], 0x0
	s_load_dwordx2 s[38:39], s[0:1], 0x130
	s_mov_b64 s[40:41], 0x400000
	s_mov_b64 s[42:43], 0x200000
	s_mov_b32 s44, 2
	v_lshlrev_b64 v[24:25], 5, v[8:9]
	v_lshlrev_b64 v[26:27], 4, v[8:9]
	s_waitcnt lgkmcnt(0)
	v_lshl_add_u64 v[24:25], v[24:25], 0, s[36:37]
	v_lshl_add_u64 v[26:27], v[26:27], 0, s[38:39]
.Lp0x_loop:
	global_load_dwordx4 v[40:43], v[24:25], off
	global_load_dwordx4 v[44:47], v[24:25], off offset:16
	v_lshl_add_u64 v[24:25], v[24:25], 0, s[40:41]
	global_load_dwordx4 v[48:51], v[24:25], off
	global_load_dwordx4 v[52:55], v[24:25], off offset:16
	v_lshl_add_u64 v[24:25], v[24:25], 0, s[40:41]
	global_load_dwordx4 v[56:59], v[24:25], off
	global_load_dwordx4 v[60:63], v[24:25], off offset:16
	v_lshl_add_u64 v[24:25], v[24:25], 0, s[40:41]
	global_load_dwordx4 v[64:67], v[24:25], off
	global_load_dwordx4 v[68:71], v[24:25], off offset:16
	v_lshl_add_u64 v[24:25], v[24:25], 0, s[40:41]
	global_load_dwordx4 v[72:75], v[24:25], off
	global_load_dwordx4 v[76:79], v[24:25], off offset:16
	v_lshl_add_u64 v[24:25], v[24:25], 0, s[40:41]
	global_load_dwordx4 v[80:83], v[24:25], off
	global_load_dwordx4 v[84:87], v[24:25], off offset:16
	v_lshl_add_u64 v[24:25], v[24:25], 0, s[40:41]
	global_load_dwordx4 v[88:91], v[24:25], off
	global_load_dwordx4 v[92:95], v[24:25], off offset:16
	v_lshl_add_u64 v[24:25], v[24:25], 0, s[40:41]
	global_load_dwordx4 v[96:99], v[24:25], off
	global_load_dwordx4 v[100:103], v[24:25], off offset:16
	v_lshl_add_u64 v[24:25], v[24:25], 0, s[40:41]
	s_waitcnt vmcnt(14)
	v_and_b32_sdwa v104, v40, v7 dst_sel:DWORD dst_unused:UNUSED_PAD src0_sel:WORD_1 src1_sel:DWORD
	v_and_b32_sdwa v105, v41, v7 dst_sel:DWORD dst_unused:UNUSED_PAD src0_sel:WORD_1 src1_sel:DWORD
	v_and_b32_sdwa v106, v42, v7 dst_sel:DWORD dst_unused:UNUSED_PAD src0_sel:WORD_1 src1_sel:DWORD
	v_and_b32_sdwa v107, v43, v7 dst_sel:DWORD dst_unused:UNUSED_PAD src0_sel:WORD_1 src1_sel:DWORD
	v_and_b32_sdwa v108, v44, v7 dst_sel:DWORD dst_unused:UNUSED_PAD src0_sel:WORD_1 src1_sel:DWORD
	v_and_b32_sdwa v109, v45, v7 dst_sel:DWORD dst_unused:UNUSED_PAD src0_sel:WORD_1 src1_sel:DWORD
	v_and_b32_sdwa v110, v46, v7 dst_sel:DWORD dst_unused:UNUSED_PAD src0_sel:WORD_1 src1_sel:DWORD
	v_and_b32_sdwa v111, v47, v7 dst_sel:DWORD dst_unused:UNUSED_PAD src0_sel:WORD_1 src1_sel:DWORD
	v_add3_u32 v40, v40, v104, s20
	v_add3_u32 v41, v41, v105, s20
	v_add3_u32 v42, v42, v106, s20
	v_add3_u32 v43, v43, v107, s20
	v_add3_u32 v44, v44, v108, s20
	v_add3_u32 v45, v45, v109, s20
	v_add3_u32 v46, v46, v110, s20
	v_add3_u32 v47, v47, v111, s20
	v_and_b32_e32 v104, 0xffff0000, v41
	v_and_b32_e32 v105, 0xffff0000, v43
	v_and_b32_e32 v106, 0xffff0000, v45
	v_and_b32_e32 v107, 0xffff0000, v47
	v_or_b32_sdwa v112, v104, v40 dst_sel:DWORD dst_unused:UNUSED_PAD src0_sel:DWORD src1_sel:WORD_1
	v_or_b32_sdwa v113, v105, v42 dst_sel:DWORD dst_unused:UNUSED_PAD src0_sel:DWORD src1_sel:WORD_1
	v_or_b32_sdwa v114, v106, v44 dst_sel:DWORD dst_unused:UNUSED_PAD src0_sel:DWORD src1_sel:WORD_1
	v_or_b32_sdwa v115, v107, v46 dst_sel:DWORD dst_unused:UNUSED_PAD src0_sel:DWORD src1_sel:WORD_1
	global_store_dwordx4 v[26:27], v[112:115], off
	v_lshl_add_u64 v[26:27], v[26:27], 0, s[42:43]
	s_waitcnt vmcnt(13)
	v_and_b32_sdwa v104, v48, v7 dst_sel:DWORD dst_unused:UNUSED_PAD src0_sel:WORD_1 src1_sel:DWORD
	v_and_b32_sdwa v105, v49, v7 dst_sel:DWORD dst_unused:UNUSED_PAD src0_sel:WORD_1 src1_sel:DWORD
	v_and_b32_sdwa v106, v50, v7 dst_sel:DWORD dst_unused:UNUSED_PAD src0_sel:WORD_1 src1_sel:DWORD
	v_and_b32_sdwa v107, v51, v7 dst_sel:DWORD dst_unused:UNUSED_PAD src0_sel:WORD_1 src1_sel:DWORD
	v_and_b32_sdwa v108, v52, v7 dst_sel:DWORD dst_unused:UNUSED_PAD src0_sel:WORD_1 src1_sel:DWORD
	v_and_b32_sdwa v109, v53, v7 dst_sel:DWORD dst_unused:UNUSED_PAD src0_sel:WORD_1 src1_sel:DWORD
	v_and_b32_sdwa v110, v54, v7 dst_sel:DWORD dst_unused:UNUSED_PAD src0_sel:WORD_1 src1_sel:DWORD
	v_and_b32_sdwa v111, v55, v7 dst_sel:DWORD dst_unused:UNUSED_PAD src0_sel:WORD_1 src1_sel:DWORD
	v_add3_u32 v48, v48, v104, s20
	v_add3_u32 v49, v49, v105, s20
	v_add3_u32 v50, v50, v106, s20
	v_add3_u32 v51, v51, v107, s20
	v_add3_u32 v52, v52, v108, s20
	v_add3_u32 v53, v53, v109, s20
	v_add3_u32 v54, v54, v110, s20
	v_add3_u32 v55, v55, v111, s20
	v_and_b32_e32 v104, 0xffff0000, v49
	v_and_b32_e32 v105, 0xffff0000, v51
	v_and_b32_e32 v106, 0xffff0000, v53
	v_and_b32_e32 v107, 0xffff0000, v55
	v_or_b32_sdwa v112, v104, v48 dst_sel:DWORD dst_unused:UNUSED_PAD src0_sel:DWORD src1_sel:WORD_1
	v_or_b32_sdwa v113, v105, v50 dst_sel:DWORD dst_unused:UNUSED_PAD src0_sel:DWORD src1_sel:WORD_1
	v_or_b32_sdwa v114, v106, v52 dst_sel:DWORD dst_unused:UNUSED_PAD src0_sel:DWORD src1_sel:WORD_1
	v_or_b32_sdwa v115, v107, v54 dst_sel:DWORD dst_unused:UNUSED_PAD src0_sel:DWORD src1_sel:WORD_1
	global_store_dwordx4 v[26:27], v[112:115], off
	v_lshl_add_u64 v[26:27], v[26:27], 0, s[42:43]
	s_waitcnt vmcnt(12)
	v_and_b32_sdwa v104, v56, v7 dst_sel:DWORD dst_unused:UNUSED_PAD src0_sel:WORD_1 src1_sel:DWORD
	v_and_b32_sdwa v105, v57, v7 dst_sel:DWORD dst_unused:UNUSED_PAD src0_sel:WORD_1 src1_sel:DWORD
	v_and_b32_sdwa v106, v58, v7 dst_sel:DWORD dst_unused:UNUSED_PAD src0_sel:WORD_1 src1_sel:DWORD
	v_and_b32_sdwa v107, v59, v7 dst_sel:DWORD dst_unused:UNUSED_PAD src0_sel:WORD_1 src1_sel:DWORD
	v_and_b32_sdwa v108, v60, v7 dst_sel:DWORD dst_unused:UNUSED_PAD src0_sel:WORD_1 src1_sel:DWORD
	v_and_b32_sdwa v109, v61, v7 dst_sel:DWORD dst_unused:UNUSED_PAD src0_sel:WORD_1 src1_sel:DWORD
	v_and_b32_sdwa v110, v62, v7 dst_sel:DWORD dst_unused:UNUSED_PAD src0_sel:WORD_1 src1_sel:DWORD
	v_and_b32_sdwa v111, v63, v7 dst_sel:DWORD dst_unused:UNUSED_PAD src0_sel:WORD_1 src1_sel:DWORD
	v_add3_u32 v56, v56, v104, s20
	v_add3_u32 v57, v57, v105, s20
	v_add3_u32 v58, v58, v106, s20
	v_add3_u32 v59, v59, v107, s20
	v_add3_u32 v60, v60, v108, s20
	v_add3_u32 v61, v61, v109, s20
	v_add3_u32 v62, v62, v110, s20
	v_add3_u32 v63, v63, v111, s20
	v_and_b32_e32 v104, 0xffff0000, v57
	v_and_b32_e32 v105, 0xffff0000, v59
	v_and_b32_e32 v106, 0xffff0000, v61
	v_and_b32_e32 v107, 0xffff0000, v63
	v_or_b32_sdwa v112, v104, v56 dst_sel:DWORD dst_unused:UNUSED_PAD src0_sel:DWORD src1_sel:WORD_1
	v_or_b32_sdwa v113, v105, v58 dst_sel:DWORD dst_unused:UNUSED_PAD src0_sel:DWORD src1_sel:WORD_1
	v_or_b32_sdwa v114, v106, v60 dst_sel:DWORD dst_unused:UNUSED_PAD src0_sel:DWORD src1_sel:WORD_1
	v_or_b32_sdwa v115, v107, v62 dst_sel:DWORD dst_unused:UNUSED_PAD src0_sel:DWORD src1_sel:WORD_1
	global_store_dwordx4 v[26:27], v[112:115], off
	v_lshl_add_u64 v[26:27], v[26:27], 0, s[42:43]
	s_waitcnt vmcnt(11)
	v_and_b32_sdwa v104, v64, v7 dst_sel:DWORD dst_unused:UNUSED_PAD src0_sel:WORD_1 src1_sel:DWORD
	v_and_b32_sdwa v105, v65, v7 dst_sel:DWORD dst_unused:UNUSED_PAD src0_sel:WORD_1 src1_sel:DWORD
	v_and_b32_sdwa v106, v66, v7 dst_sel:DWORD dst_unused:UNUSED_PAD src0_sel:WORD_1 src1_sel:DWORD
	v_and_b32_sdwa v107, v67, v7 dst_sel:DWORD dst_unused:UNUSED_PAD src0_sel:WORD_1 src1_sel:DWORD
	v_and_b32_sdwa v108, v68, v7 dst_sel:DWORD dst_unused:UNUSED_PAD src0_sel:WORD_1 src1_sel:DWORD
	v_and_b32_sdwa v109, v69, v7 dst_sel:DWORD dst_unused:UNUSED_PAD src0_sel:WORD_1 src1_sel:DWORD
	v_and_b32_sdwa v110, v70, v7 dst_sel:DWORD dst_unused:UNUSED_PAD src0_sel:WORD_1 src1_sel:DWORD
	v_and_b32_sdwa v111, v71, v7 dst_sel:DWORD dst_unused:UNUSED_PAD src0_sel:WORD_1 src1_sel:DWORD
	v_add3_u32 v64, v64, v104, s20
	v_add3_u32 v65, v65, v105, s20
	v_add3_u32 v66, v66, v106, s20
	v_add3_u32 v67, v67, v107, s20
	v_add3_u32 v68, v68, v108, s20
	v_add3_u32 v69, v69, v109, s20
	v_add3_u32 v70, v70, v110, s20
	v_add3_u32 v71, v71, v111, s20
	v_and_b32_e32 v104, 0xffff0000, v65
	v_and_b32_e32 v105, 0xffff0000, v67
	v_and_b32_e32 v106, 0xffff0000, v69
	v_and_b32_e32 v107, 0xffff0000, v71
	v_or_b32_sdwa v112, v104, v64 dst_sel:DWORD dst_unused:UNUSED_PAD src0_sel:DWORD src1_sel:WORD_1
	v_or_b32_sdwa v113, v105, v66 dst_sel:DWORD dst_unused:UNUSED_PAD src0_sel:DWORD src1_sel:WORD_1
	v_or_b32_sdwa v114, v106, v68 dst_sel:DWORD dst_unused:UNUSED_PAD src0_sel:DWORD src1_sel:WORD_1
	v_or_b32_sdwa v115, v107, v70 dst_sel:DWORD dst_unused:UNUSED_PAD src0_sel:DWORD src1_sel:WORD_1
	global_store_dwordx4 v[26:27], v[112:115], off
	v_lshl_add_u64 v[26:27], v[26:27], 0, s[42:43]
	s_waitcnt vmcnt(10)
	v_and_b32_sdwa v104, v72, v7 dst_sel:DWORD dst_unused:UNUSED_PAD src0_sel:WORD_1 src1_sel:DWORD
	v_and_b32_sdwa v105, v73, v7 dst_sel:DWORD dst_unused:UNUSED_PAD src0_sel:WORD_1 src1_sel:DWORD
	v_and_b32_sdwa v106, v74, v7 dst_sel:DWORD dst_unused:UNUSED_PAD src0_sel:WORD_1 src1_sel:DWORD
	v_and_b32_sdwa v107, v75, v7 dst_sel:DWORD dst_unused:UNUSED_PAD src0_sel:WORD_1 src1_sel:DWORD
	v_and_b32_sdwa v108, v76, v7 dst_sel:DWORD dst_unused:UNUSED_PAD src0_sel:WORD_1 src1_sel:DWORD
	v_and_b32_sdwa v109, v77, v7 dst_sel:DWORD dst_unused:UNUSED_PAD src0_sel:WORD_1 src1_sel:DWORD
	v_and_b32_sdwa v110, v78, v7 dst_sel:DWORD dst_unused:UNUSED_PAD src0_sel:WORD_1 src1_sel:DWORD
	v_and_b32_sdwa v111, v79, v7 dst_sel:DWORD dst_unused:UNUSED_PAD src0_sel:WORD_1 src1_sel:DWORD
	v_add3_u32 v72, v72, v104, s20
	v_add3_u32 v73, v73, v105, s20
	v_add3_u32 v74, v74, v106, s20
	v_add3_u32 v75, v75, v107, s20
	v_add3_u32 v76, v76, v108, s20
	v_add3_u32 v77, v77, v109, s20
	v_add3_u32 v78, v78, v110, s20
	v_add3_u32 v79, v79, v111, s20
	v_and_b32_e32 v104, 0xffff0000, v73
	v_and_b32_e32 v105, 0xffff0000, v75
	v_and_b32_e32 v106, 0xffff0000, v77
	v_and_b32_e32 v107, 0xffff0000, v79
	v_or_b32_sdwa v112, v104, v72 dst_sel:DWORD dst_unused:UNUSED_PAD src0_sel:DWORD src1_sel:WORD_1
	v_or_b32_sdwa v113, v105, v74 dst_sel:DWORD dst_unused:UNUSED_PAD src0_sel:DWORD src1_sel:WORD_1
	v_or_b32_sdwa v114, v106, v76 dst_sel:DWORD dst_unused:UNUSED_PAD src0_sel:DWORD src1_sel:WORD_1
	v_or_b32_sdwa v115, v107, v78 dst_sel:DWORD dst_unused:UNUSED_PAD src0_sel:DWORD src1_sel:WORD_1
	global_store_dwordx4 v[26:27], v[112:115], off
	v_lshl_add_u64 v[26:27], v[26:27], 0, s[42:43]
	s_waitcnt vmcnt(9)
	v_and_b32_sdwa v104, v80, v7 dst_sel:DWORD dst_unused:UNUSED_PAD src0_sel:WORD_1 src1_sel:DWORD
	v_and_b32_sdwa v105, v81, v7 dst_sel:DWORD dst_unused:UNUSED_PAD src0_sel:WORD_1 src1_sel:DWORD
	v_and_b32_sdwa v106, v82, v7 dst_sel:DWORD dst_unused:UNUSED_PAD src0_sel:WORD_1 src1_sel:DWORD
	v_and_b32_sdwa v107, v83, v7 dst_sel:DWORD dst_unused:UNUSED_PAD src0_sel:WORD_1 src1_sel:DWORD
	v_and_b32_sdwa v108, v84, v7 dst_sel:DWORD dst_unused:UNUSED_PAD src0_sel:WORD_1 src1_sel:DWORD
	v_and_b32_sdwa v109, v85, v7 dst_sel:DWORD dst_unused:UNUSED_PAD src0_sel:WORD_1 src1_sel:DWORD
	v_and_b32_sdwa v110, v86, v7 dst_sel:DWORD dst_unused:UNUSED_PAD src0_sel:WORD_1 src1_sel:DWORD
	v_and_b32_sdwa v111, v87, v7 dst_sel:DWORD dst_unused:UNUSED_PAD src0_sel:WORD_1 src1_sel:DWORD
	v_add3_u32 v80, v80, v104, s20
	v_add3_u32 v81, v81, v105, s20
	v_add3_u32 v82, v82, v106, s20
	v_add3_u32 v83, v83, v107, s20
	v_add3_u32 v84, v84, v108, s20
	v_add3_u32 v85, v85, v109, s20
	v_add3_u32 v86, v86, v110, s20
	v_add3_u32 v87, v87, v111, s20
	v_and_b32_e32 v104, 0xffff0000, v81
	v_and_b32_e32 v105, 0xffff0000, v83
	v_and_b32_e32 v106, 0xffff0000, v85
	v_and_b32_e32 v107, 0xffff0000, v87
	v_or_b32_sdwa v112, v104, v80 dst_sel:DWORD dst_unused:UNUSED_PAD src0_sel:DWORD src1_sel:WORD_1
	v_or_b32_sdwa v113, v105, v82 dst_sel:DWORD dst_unused:UNUSED_PAD src0_sel:DWORD src1_sel:WORD_1
	v_or_b32_sdwa v114, v106, v84 dst_sel:DWORD dst_unused:UNUSED_PAD src0_sel:DWORD src1_sel:WORD_1
	v_or_b32_sdwa v115, v107, v86 dst_sel:DWORD dst_unused:UNUSED_PAD src0_sel:DWORD src1_sel:WORD_1
	global_store_dwordx4 v[26:27], v[112:115], off
	v_lshl_add_u64 v[26:27], v[26:27], 0, s[42:43]
	s_waitcnt vmcnt(8)
	v_and_b32_sdwa v104, v88, v7 dst_sel:DWORD dst_unused:UNUSED_PAD src0_sel:WORD_1 src1_sel:DWORD
	v_and_b32_sdwa v105, v89, v7 dst_sel:DWORD dst_unused:UNUSED_PAD src0_sel:WORD_1 src1_sel:DWORD
	v_and_b32_sdwa v106, v90, v7 dst_sel:DWORD dst_unused:UNUSED_PAD src0_sel:WORD_1 src1_sel:DWORD
	v_and_b32_sdwa v107, v91, v7 dst_sel:DWORD dst_unused:UNUSED_PAD src0_sel:WORD_1 src1_sel:DWORD
	v_and_b32_sdwa v108, v92, v7 dst_sel:DWORD dst_unused:UNUSED_PAD src0_sel:WORD_1 src1_sel:DWORD
	v_and_b32_sdwa v109, v93, v7 dst_sel:DWORD dst_unused:UNUSED_PAD src0_sel:WORD_1 src1_sel:DWORD
	v_and_b32_sdwa v110, v94, v7 dst_sel:DWORD dst_unused:UNUSED_PAD src0_sel:WORD_1 src1_sel:DWORD
	v_and_b32_sdwa v111, v95, v7 dst_sel:DWORD dst_unused:UNUSED_PAD src0_sel:WORD_1 src1_sel:DWORD
	v_add3_u32 v88, v88, v104, s20
	v_add3_u32 v89, v89, v105, s20
	v_add3_u32 v90, v90, v106, s20
	v_add3_u32 v91, v91, v107, s20
	v_add3_u32 v92, v92, v108, s20
	v_add3_u32 v93, v93, v109, s20
	v_add3_u32 v94, v94, v110, s20
	v_add3_u32 v95, v95, v111, s20
	v_and_b32_e32 v104, 0xffff0000, v89
	v_and_b32_e32 v105, 0xffff0000, v91
	v_and_b32_e32 v106, 0xffff0000, v93
	v_and_b32_e32 v107, 0xffff0000, v95
	v_or_b32_sdwa v112, v104, v88 dst_sel:DWORD dst_unused:UNUSED_PAD src0_sel:DWORD src1_sel:WORD_1
	v_or_b32_sdwa v113, v105, v90 dst_sel:DWORD dst_unused:UNUSED_PAD src0_sel:DWORD src1_sel:WORD_1
	v_or_b32_sdwa v114, v106, v92 dst_sel:DWORD dst_unused:UNUSED_PAD src0_sel:DWORD src1_sel:WORD_1
	v_or_b32_sdwa v115, v107, v94 dst_sel:DWORD dst_unused:UNUSED_PAD src0_sel:DWORD src1_sel:WORD_1
	global_store_dwordx4 v[26:27], v[112:115], off
	v_lshl_add_u64 v[26:27], v[26:27], 0, s[42:43]
	s_waitcnt vmcnt(7)
	v_and_b32_sdwa v104, v96, v7 dst_sel:DWORD dst_unused:UNUSED_PAD src0_sel:WORD_1 src1_sel:DWORD
	v_and_b32_sdwa v105, v97, v7 dst_sel:DWORD dst_unused:UNUSED_PAD src0_sel:WORD_1 src1_sel:DWORD
	v_and_b32_sdwa v106, v98, v7 dst_sel:DWORD dst_unused:UNUSED_PAD src0_sel:WORD_1 src1_sel:DWORD
	v_and_b32_sdwa v107, v99, v7 dst_sel:DWORD dst_unused:UNUSED_PAD src0_sel:WORD_1 src1_sel:DWORD
	v_and_b32_sdwa v108, v100, v7 dst_sel:DWORD dst_unused:UNUSED_PAD src0_sel:WORD_1 src1_sel:DWORD
	v_and_b32_sdwa v109, v101, v7 dst_sel:DWORD dst_unused:UNUSED_PAD src0_sel:WORD_1 src1_sel:DWORD
	v_and_b32_sdwa v110, v102, v7 dst_sel:DWORD dst_unused:UNUSED_PAD src0_sel:WORD_1 src1_sel:DWORD
	v_and_b32_sdwa v111, v103, v7 dst_sel:DWORD dst_unused:UNUSED_PAD src0_sel:WORD_1 src1_sel:DWORD
	v_add3_u32 v96, v96, v104, s20
	v_add3_u32 v97, v97, v105, s20
	v_add3_u32 v98, v98, v106, s20
	v_add3_u32 v99, v99, v107, s20
	v_add3_u32 v100, v100, v108, s20
	v_add3_u32 v101, v101, v109, s20
	v_add3_u32 v102, v102, v110, s20
	v_add3_u32 v103, v103, v111, s20
	v_and_b32_e32 v104, 0xffff0000, v97
	v_and_b32_e32 v105, 0xffff0000, v99
	v_and_b32_e32 v106, 0xffff0000, v101
	v_and_b32_e32 v107, 0xffff0000, v103
	v_or_b32_sdwa v112, v104, v96 dst_sel:DWORD dst_unused:UNUSED_PAD src0_sel:DWORD src1_sel:WORD_1
	v_or_b32_sdwa v113, v105, v98 dst_sel:DWORD dst_unused:UNUSED_PAD src0_sel:DWORD src1_sel:WORD_1
	v_or_b32_sdwa v114, v106, v100 dst_sel:DWORD dst_unused:UNUSED_PAD src0_sel:DWORD src1_sel:WORD_1
	v_or_b32_sdwa v115, v107, v102 dst_sel:DWORD dst_unused:UNUSED_PAD src0_sel:DWORD src1_sel:WORD_1
	global_store_dwordx4 v[26:27], v[112:115], off
	v_lshl_add_u64 v[26:27], v[26:27], 0, s[42:43]
	s_sub_u32 s44, s44, 1
	s_cmp_lg_u32 s44, 0
	s_cbranch_scc1 .Lp0x_loop
	s_mov_b64 s[36:37], 0x200000
	v_lshl_add_u64 v[14:15], v[8:9], 0, s[36:37]
	s_mov_b64 s[36:37], 0x208000
	v_cmp_gt_u64_e32 vcc, s[36:37], v[14:15]
	s_nop 1
	s_and_b64 exec, exec, vcc
	s_cbranch_execz .LBB0_14
	s_branch .LBB0_9

.LBB0_569:
	s_ashr_i32 s10, s35, 4
	s_and_b32 s44, s10, 3
	v_cvt_f32_ubyte0_e32 v2, s44
	v_sub_f32_e32 v2, 0xc0a00000, v2
	v_cmp_gt_f32_e32 vcc, s30, v2
	s_lshl_b32 s8, s26, 1
	s_and_b32 s12, s24, 0xfffff000
	v_cndmask_b32_e32 v3, 0, v1, vcc
	s_and_b32 s11, s8, 0x100
	s_lshl_b32 s8, s26, 10
	v_add_f32_e32 v2, v2, v3
	s_ashr_i32 s13, s12, 31
	s_and_b32 s39, s8, 0x20000
	s_lshl_b32 s8, s24, 1
	v_exp_f32_e32 v2, v2
	s_lshl_b64 s[16:17], s[12:13], 11
	s_and_b32 s38, s8, 0x380
	s_lshl_b64 s[18:19], s[12:13], 12
	s_and_b64 s[12:13], vcc, exec
	s_cselect_b32 s8, 0xffffffc0, 0
	v_ldexp_f32 v2, v2, s8
	v_sub_f32_e32 v2, 1.0, v2
	s_mov_b32 s8, 0x800000
	v_cmp_gt_f32_e32 vcc, s8, v2
	s_and_b64 s[12:13], vcc, exec
	v_mov_b32_e32 v20, v0
	s_cselect_b32 s8, 32, 0
	s_lshl_b32 s13, s35, 6
	v_readfirstlane_b32 s40, v20
	v_ldexp_f32 v2, v2, s8
	s_ashr_i32 s8, s40, 2
	s_and_b32 s14, s13, 0xfffff000
	s_and_b32 s12, s8, 0xffffffe0
	s_lshr_b32 s8, s40, 1
	s_ashr_i32 s15, s14, 31
	v_readlane_b32 s60, v251, 19
	s_and_b32 s36, s8, 32
	s_lshl_b64 s[42:43], s[14:15], 11
	v_readlane_b32 s62, v251, 21
	v_log_f32_e32 v2, v2
	v_readlane_b32 s63, v251, 22
	s_add_u32 s8, s62, s42
	s_addc_u32 s37, s63, s43
	s_lshl_b32 s41, s44, 9
	s_add_u32 s42, s8, s41
	v_cndmask_b32_e32 v3, 0, v49, vcc
	s_addc_u32 s37, s37, 0
	s_lshl_b32 s8, s35, 4
	v_sub_f32_e32 v51, v2, v3
	v_bfe_u32 v73, v20, 5, 1
	v_bfe_u32 v2, v20, 2, 2
	s_and_b32 s8, s8, 0x80
	v_lshl_or_b32 v56, v73, 3, v2
	v_lshlrev_b32_e32 v2, 2, v20
	s_lshl_b32 s43, s8, 1
	v_and_b32_e32 v3, 16, v20
	v_and_b32_e32 v2, 12, v2
	s_add_u32 s42, s42, s43
	v_lshlrev_b32_e32 v35, 4, v20
	v_or3_b32 v4, v3, s12, v2
	v_or3_b32 v21, v3, s36, v2
	s_addc_u32 s43, s37, 0
	v_and_b32_e32 v2, 0xf0, v35
	v_mov_b32_e32 v3, v47
	v_lshlrev_b32_e32 v74, 1, v4
	v_lshl_add_u64 v[4:5], s[42:43], 0, v[2:3]
	v_ashrrev_i32_e32 v6, 4, v20
	v_add_u32_e32 v3, 0x200, v20
	v_ashrrev_i32_e32 v7, 31, v6
	v_ashrrev_i32_e32 v12, 4, v3
	v_lshlrev_b64 v[8:9], 11, v[6:7]
	v_ashrrev_i32_e32 v13, 31, v12
	v_readlane_b32 s64, v251, 23
	s_lshl_b64 s[14:15], s[14:15], 12
	s_and_b32 s37, s13, 0x1c0
	v_lshl_add_u64 v[10:11], v[4:5], 0, v[8:9]
	v_lshlrev_b64 v[14:15], 11, v[12:13]
	v_add_u32_e32 v7, 0x400, v20
	v_readlane_b32 s65, v251, 24
	v_lshl_add_u64 v[16:17], v[4:5], 0, v[14:15]
	global_load_dwordx4 v[22:25], v[10:11], off
	global_load_dwordx4 v[26:29], v[16:17], off
	v_ashrrev_i32_e32 v10, 4, v7
	v_add_u32_e32 v7, 0x600, v20
	s_add_u32 s13, s64, s14
	v_ashrrev_i32_e32 v42, 4, v7
	s_addc_u32 s14, s65, s15
	s_lshl_b32 s46, s44, 10
	v_ashrrev_i32_e32 v11, 31, v10
	v_ashrrev_i32_e32 v43, 31, v42
	s_add_u32 s13, s13, s46
	v_lshlrev_b64 v[16:17], 11, v[10:11]
	v_lshlrev_b64 v[44:45], 11, v[42:43]
	s_addc_u32 s15, s14, 0
	s_lshl_b32 s14, s37, 1
	v_lshl_add_u64 v[18:19], v[4:5], 0, v[16:17]
	v_lshl_add_u64 v[4:5], v[4:5], 0, v[44:45]
	s_add_u32 s14, s13, s14
	v_ashrrev_i32_e32 v54, 3, v20
	v_ashrrev_i32_e32 v58, 3, v3
	global_load_dwordx4 v[30:33], v[18:19], off
	global_load_dwordx4 v[38:41], v[4:5], off
	s_addc_u32 s15, s15, 0
	v_and_b32_e32 v4, 0x70, v35
	v_mov_b32_e32 v5, v47
	v_ashrrev_i32_e32 v55, 31, v54
	v_ashrrev_i32_e32 v59, 31, v58
	v_lshl_add_u64 v[18:19], s[14:15], 0, v[4:5]
	v_lshlrev_b64 v[68:69], 12, v[54:55]
	v_lshlrev_b64 v[66:67], 12, v[58:59]
	v_and_b32_e32 v48, 31, v20
	v_mul_f32_e32 v34, 0x43000000, v51
	v_lshlrev_b32_e32 v11, 1, v21
	v_lshl_add_u64 v[20:21], v[18:19], 0, v[68:69]
	v_lshl_add_u64 v[18:19], v[18:19], 0, v[66:67]
	v_cmp_gt_f32_e32 vcc, s30, v34
	global_load_dwordx4 v[34:37], v[20:21], off
	s_nop 0
	global_load_dwordx4 v[18:21], v[18:19], off
	v_mad_u32_u24 v43, v56, s31, 0
	v_lshlrev_b32_e32 v5, 7, v56
	v_sub_u32_e32 v82, v43, v5
	v_sub_u32_e32 v5, 0x7f, v54
	v_cvt_f32_i32_e32 v5, v5
	v_sub_u32_e32 v7, 0x7f, v58
	v_cvt_f32_i32_e32 v7, v7
	v_mul_lo_u32 v75, v6, s31
	v_mul_f32_e32 v6, v51, v5
	v_cndmask_b32_e32 v3, 0, v1, vcc
	s_and_b64 s[14:15], vcc, exec
	v_cmp_gt_f32_e32 vcc, s30, v6
	v_mul_f32_e32 v55, v51, v7
	v_fmac_f32_e32 v3, 0x43000000, v51
	v_cndmask_b32_e32 v6, 0, v1, vcc
	v_fmac_f32_e32 v6, v51, v5
	v_exp_f32_e32 v5, v6
	v_cndmask_b32_e32 v6, 0, v72, vcc
	v_cmp_gt_f32_e32 vcc, s30, v55
	v_exp_f32_e32 v3, v3
	v_ldexp_f32 v56, v5, v6
	v_cndmask_b32_e32 v55, 0, v1, vcc
	v_fmac_f32_e32 v55, v51, v7
	v_exp_f32_e32 v7, v55
	v_cndmask_b32_e32 v5, 0, v72, vcc
	v_mul_lo_u32 v51, v54, s33
	s_cselect_b32 s13, 0xffffffc0, 0
	v_ldexp_f32 v54, v7, v5
	v_lshl_add_u64 v[6:7], v[8:9], 0, s[16:17]
	v_or_b32_e32 v5, s41, v6
	v_or3_b32 v6, v5, s11, v2
	s_lshl_b32 s14, s10, 5
	v_mul_lo_u32 v76, v58, s33
	v_lshl_add_u64 v[58:59], s[0:1], 0, v[6:7]
	v_lshl_add_u64 v[6:7], v[14:15], 0, s[16:17]
	v_or_b32_e32 v5, s41, v6
	s_ashr_i32 s15, s14, 31
	v_ldexp_f32 v50, v3, s13
	s_ashr_i32 s13, s12, 31
	v_or3_b32 v6, v5, s11, v2
	s_lshl_b64 s[42:43], s[14:15], 18
	v_lshl_add_u64 v[60:61], s[0:1], 0, v[6:7]
	v_lshl_add_u64 v[6:7], v[16:17], 0, s[16:17]
	s_or_b32 s15, s42, s39
	s_lshl_b64 s[44:45], s[12:13], 10
	v_lshlrev_b32_e32 v46, 12, v73
	v_or_b32_e32 v5, s41, v6
	s_add_u32 s15, s44, s15
	v_or3_b32 v6, v5, s11, v2
	v_or_b32_e32 v5, s15, v46
	v_lshl_add_u64 v[62:63], s[0:1], 0, v[6:7]
	s_addc_u32 s39, s45, s43
	v_or_b32_e32 v5, s38, v5
	s_and_b32 s15, s40, 64
	v_lshlrev_b32_e32 v6, 1, v48
	v_or3_b32 v6, v5, s15, v6
	v_mov_b32_e32 v7, s39
	v_lshl_add_u64 v[64:65], s[58:59], 0, v[6:7]
	v_lshl_add_u64 v[6:7], v[66:67], 0, s[18:19]
	v_or_b32_e32 v5, s46, v6
	v_or3_b32 v6, v5, s38, v4
	v_lshl_add_u64 v[66:67], s[6:7], 0, v[6:7]
	v_lshl_add_u64 v[6:7], v[68:69], 0, s[18:19]
	v_or_b32_e32 v5, s46, v6
	v_add_u32_e32 v13, 0, v4
	v_or3_b32 v6, v5, s38, v4
	v_lshl_add_u64 v[4:5], v[44:45], 0, s[16:17]
	v_or_b32_e32 v4, s41, v4
	v_add_u32_e32 v3, 0, v2
	v_mul_lo_u32 v12, v12, s31
	v_mul_lo_u32 v10, v10, s31
	v_mul_lo_u32 v42, v42, s31
	v_or3_b32 v4, v4, s11, v2
	v_mov_b32_e32 v52, v50
	v_mov_b32_e32 v53, v50
	v_mov_b32_e32 v57, v56
	v_mov_b32_e32 v55, v54
	v_lshl_add_u64 v[68:69], s[6:7], 0, v[6:7]
	v_lshl_add_u64 v[70:71], s[0:1], 0, v[4:5]
	s_mov_b64 s[16:17], 0
	v_add_u32_e32 v78, v3, v75
	v_add_u32_e32 v79, v3, v12
	v_add_u32_e32 v80, v3, v10
	v_add_u32_e32 v81, v3, v42
	v_add_u32_e32 v77, v13, v51
	v_add_u32_e32 v76, v13, v76
	v_add_u32_e32 v75, v43, v74
	v_add_u32_e32 v74, v82, v11
	v_mov_b32_e32 v2, v47
	v_mov_b32_e32 v3, v47
	v_mov_b32_e32 v4, v47
	v_mov_b32_e32 v5, v47
	v_mov_b32_e32 v6, v47
	v_mov_b32_e32 v7, v47
	v_mov_b32_e32 v8, v47
	v_mov_b32_e32 v9, v47
	v_mov_b32_e32 v10, v47
	v_mov_b32_e32 v11, v47
	v_mov_b32_e32 v12, v47
	v_mov_b32_e32 v13, v47
	v_mov_b32_e32 v14, v47
	v_mov_b32_e32 v15, v47
	v_mov_b32_e32 v16, v47
	v_mov_b32_e32 v17, v47
	v_readlane_b32 s61, v251, 20
	v_readlane_b32 s66, v251, 25
	v_readlane_b32 s67, v251, 26
	v_readlane_b32 s68, v251, 27
	v_readlane_b32 s69, v251, 28
	v_readlane_b32 s70, v251, 29
	v_readlane_b32 s71, v251, 30
	v_readlane_b32 s72, v251, 31
	v_readlane_b32 s73, v251, 32
	v_readlane_b32 s74, v251, 33
	v_readlane_b32 s75, v251, 34
	v_lshl_add_u64 v[112:113], v[58:59], 0, s[16:17]
	global_load_dwordx4 v[88:91], v[112:113], off
	v_lshl_add_u64 v[114:115], v[60:61], 0, s[16:17]
	global_load_dwordx4 v[92:95], v[114:115], off
	v_lshl_add_u64 v[112:113], v[62:63], 0, s[16:17]
	global_load_dwordx4 v[96:99], v[112:113], off
	v_lshl_add_u64 v[114:115], v[70:71], 0, s[16:17]
	global_load_dwordx4 v[100:103], v[114:115], off
	global_load_dwordx4 v[104:107], v[68:69], off
	global_load_dwordx4 v[108:111], v[66:67], off
	s_waitcnt vmcnt(6)
.LBB0_570:
	s_nop 0
	ds_write_b128 v78, v[22:25]
	s_nop 0
	ds_write_b128 v79, v[26:29]
	s_nop 0
	ds_write_b128 v80, v[30:33]
	s_nop 0
	ds_write_b128 v81, v[38:41]
	s_nop 0
	v_lshlrev_b32_e32 v22, 16, v34
	v_and_b32_e32 v23, 0xffff0000, v34
	v_lshlrev_b32_e32 v24, 16, v35
	v_and_b32_e32 v25, 0xffff0000, v35
	v_pk_mul_f32 v[22:23], v[56:57], v[22:23]
	v_pk_mul_f32 v[24:25], v[56:57], v[24:25]
	v_cvt_pk_bf16_f32 v22, v22, v23
	v_cvt_pk_bf16_f32 v23, v24, v25
	v_lshlrev_b32_e32 v24, 16, v36
	v_and_b32_e32 v25, 0xffff0000, v36
	v_lshlrev_b32_e32 v26, 16, v37
	v_and_b32_e32 v27, 0xffff0000, v37
	v_pk_mul_f32 v[24:25], v[56:57], v[24:25]
	v_pk_mul_f32 v[26:27], v[56:57], v[26:27]
	v_cvt_pk_bf16_f32 v24, v24, v25
	v_cvt_pk_bf16_f32 v25, v26, v27
	ds_write_b128 v77, v[22:25] offset:40960
	s_nop 0
	v_lshlrev_b32_e32 v22, 16, v18
	v_and_b32_e32 v23, 0xffff0000, v18
	v_pk_mul_f32 v[22:23], v[54:55], v[22:23]
	v_cvt_pk_bf16_f32 v44, v2, s0
	v_cvt_pk_bf16_f32 v18, v22, v23
	v_lshlrev_b32_e32 v22, 16, v19
	v_and_b32_e32 v23, 0xffff0000, v19
	v_pk_mul_f32 v[22:23], v[54:55], v[22:23]
	v_lshl_add_u64 v[42:43], v[64:65], 0, s[16:17]
	v_cvt_pk_bf16_f32 v19, v22, v23
	v_lshlrev_b32_e32 v22, 16, v20
	v_and_b32_e32 v23, 0xffff0000, v20
	v_pk_mul_f32 v[22:23], v[54:55], v[22:23]
	s_movk_i32 s11, 0x2000
	v_cvt_pk_bf16_f32 v20, v22, v23
	v_lshlrev_b32_e32 v22, 16, v21
	v_and_b32_e32 v23, 0xffff0000, v21
	v_pk_mul_f32 v[22:23], v[54:55], v[22:23]
	v_cvt_pk_bf16_f32 v51, v6, s0
	v_cvt_pk_bf16_f32 v21, v22, v23
	ds_write_b128 v76, v[18:21] offset:40960
	s_waitcnt lgkmcnt(0)
	s_barrier
	s_add_u32 s16, s16, 0x40000
	s_addc_u32 s17, s17, 0
	global_store_short v[42:43], v44, off
	v_cvt_pk_bf16_f32 v44, v3, s0
	global_store_short v[42:43], v44, off offset:1024
	v_cvt_pk_bf16_f32 v44, v4, s0
	global_store_short v[42:43], v44, off offset:2048
	v_cvt_pk_bf16_f32 v44, v5, s0
	global_store_short v[42:43], v44, off offset:3072
	v_add_co_u32_e32 v44, vcc, s11, v42
	s_movk_i32 s11, 0x6000
	s_nop 0
	v_addc_co_u32_e32 v45, vcc, 0, v43, vcc
	global_store_short v[44:45], v51, off
	v_cvt_pk_bf16_f32 v51, v7, s0
	global_store_short v[44:45], v51, off offset:1024
	v_cvt_pk_bf16_f32 v51, v8, s0
	global_store_short v[44:45], v51, off offset:2048
	v_cvt_pk_bf16_f32 v51, v9, s0
	global_store_short v[44:45], v51, off offset:3072
	v_add_co_u32_e32 v44, vcc, s34, v42
	v_cvt_pk_bf16_f32 v51, v10, s0
	s_nop 0
	v_addc_co_u32_e32 v45, vcc, 0, v43, vcc
	global_store_short v[44:45], v51, off
	v_cvt_pk_bf16_f32 v51, v11, s0
	global_store_short v[44:45], v51, off offset:1024
	v_cvt_pk_bf16_f32 v51, v12, s0
	global_store_short v[44:45], v51, off offset:2048
	v_cvt_pk_bf16_f32 v51, v13, s0
	v_add_co_u32_e32 v42, vcc, s11, v42
	global_store_short v[44:45], v51, off offset:3072
	v_cvt_pk_bf16_f32 v44, v14, s0
	v_addc_co_u32_e32 v43, vcc, 0, v43, vcc
	global_store_short v[42:43], v44, off
	v_cvt_pk_bf16_f32 v44, v15, s0
	global_store_short v[42:43], v44, off offset:1024
	v_cvt_pk_bf16_f32 v44, v16, s0
	global_store_short v[42:43], v44, off offset:2048
	v_cvt_pk_bf16_f32 v44, v17, s0
	global_store_short v[42:43], v44, off offset:3072
	v_lshl_add_u64 v[66:67], v[66:67], 0, s[4:5]
	v_lshl_add_u64 v[68:69], v[68:69], 0, s[4:5]
	s_waitcnt vmcnt(16)
	v_mov_b32_e32 v22, v88
	v_mov_b32_e32 v23, v89
	v_mov_b32_e32 v24, v90
	v_mov_b32_e32 v25, v91
	v_mov_b32_e32 v26, v92
	v_mov_b32_e32 v27, v93
	v_mov_b32_e32 v28, v94
	v_mov_b32_e32 v29, v95
	v_mov_b32_e32 v30, v96
	v_mov_b32_e32 v31, v97
	v_mov_b32_e32 v32, v98
	v_mov_b32_e32 v33, v99
	v_mov_b32_e32 v38, v100
	v_mov_b32_e32 v39, v101
	v_mov_b32_e32 v40, v102
	v_mov_b32_e32 v41, v103
	v_mov_b32_e32 v34, v104
	v_mov_b32_e32 v35, v105
	v_mov_b32_e32 v36, v106
	v_mov_b32_e32 v37, v107
	v_mov_b32_e32 v18, v108
	v_mov_b32_e32 v19, v109
	v_mov_b32_e32 v20, v110
	v_mov_b32_e32 v21, v111
	s_cmp_eq_u32 s16, 0x7c0000
	s_cbranch_scc1 .Lrs_skipld
	v_lshl_add_u64 v[112:113], v[58:59], 0, s[16:17]
	global_load_dwordx4 v[88:91], v[112:113], off
	v_lshl_add_u64 v[114:115], v[60:61], 0, s[16:17]
	global_load_dwordx4 v[92:95], v[114:115], off
	v_lshl_add_u64 v[112:113], v[62:63], 0, s[16:17]
	global_load_dwordx4 v[96:99], v[112:113], off
	v_lshl_add_u64 v[114:115], v[70:71], 0, s[16:17]
	global_load_dwordx4 v[100:103], v[114:115], off
	global_load_dwordx4 v[104:107], v[68:69], off
	global_load_dwordx4 v[108:111], v[66:67], off
.Lrs_skipld:
	ds_read_b64_tr_b16 v[42:43], v75
	ds_read_b64_tr_b16 v[44:45], v75 offset:1280
	ds_read_b64_tr_b16 v[82:83], v74 offset:40960
	ds_read_b64_tr_b16 v[84:85], v74 offset:41728
	v_mov_b32_e32 v51, v50
	v_pk_mul_f32 v[16:17], v[50:51], v[16:17]
	v_pk_mul_f32 v[14:15], v[50:51], v[14:15]
	v_pk_mul_f32 v[12:13], v[50:51], v[12:13]
	v_pk_mul_f32 v[10:11], v[50:51], v[10:11]
	v_pk_mul_f32 v[8:9], v[50:51], v[8:9]
	v_pk_mul_f32 v[6:7], v[50:51], v[6:7]
	v_pk_mul_f32 v[4:5], v[50:51], v[4:5]
	v_pk_mul_f32 v[2:3], v[52:53], v[2:3]
	s_nop 0
	s_nop 0
	s_waitcnt lgkmcnt(0)
	v_mfma_f32_32x32x16_bf16 v[2:17], v[42:45], v[82:85], v[2:17]
	ds_read_b64_tr_b16 v[42:43], v75 offset:5120
	ds_read_b64_tr_b16 v[44:45], v75 offset:6400
	ds_read_b64_tr_b16 v[82:83], v74 offset:44032
	ds_read_b64_tr_b16 v[84:85], v74 offset:44800
	s_nop 0
	s_cmp_lg_u32 s16, 0x7c0000
	s_waitcnt lgkmcnt(0)
	v_mfma_f32_32x32x16_bf16 v[2:17], v[42:45], v[82:85], v[2:17]
	ds_read_b64_tr_b16 v[42:43], v75 offset:10240
	ds_read_b64_tr_b16 v[44:45], v75 offset:11520
	ds_read_b64_tr_b16 v[82:83], v74 offset:47104
	ds_read_b64_tr_b16 v[84:85], v74 offset:47872
	s_waitcnt lgkmcnt(0)
	v_mfma_f32_32x32x16_bf16 v[2:17], v[42:45], v[82:85], v[2:17]
	ds_read_b64_tr_b16 v[42:43], v75 offset:15360
	ds_read_b64_tr_b16 v[44:45], v75 offset:16640
	ds_read_b64_tr_b16 v[82:83], v74 offset:50176
	ds_read_b64_tr_b16 v[84:85], v74 offset:50944
	s_waitcnt lgkmcnt(0)
	v_mfma_f32_32x32x16_bf16 v[2:17], v[42:45], v[82:85], v[2:17]
	ds_read_b64_tr_b16 v[42:43], v75 offset:20480
	ds_read_b64_tr_b16 v[44:45], v75 offset:21760
	ds_read_b64_tr_b16 v[82:83], v74 offset:53248
	ds_read_b64_tr_b16 v[84:85], v74 offset:54016
	s_waitcnt lgkmcnt(0)
	v_mfma_f32_32x32x16_bf16 v[2:17], v[42:45], v[82:85], v[2:17]
	ds_read_b64_tr_b16 v[42:43], v75 offset:25600
	ds_read_b64_tr_b16 v[44:45], v75 offset:26880
	ds_read_b64_tr_b16 v[82:83], v74 offset:56320
	ds_read_b64_tr_b16 v[84:85], v74 offset:57088
	s_waitcnt lgkmcnt(0)
	v_mfma_f32_32x32x16_bf16 v[2:17], v[42:45], v[82:85], v[2:17]
	ds_read_b64_tr_b16 v[42:43], v75 offset:30720
	ds_read_b64_tr_b16 v[44:45], v75 offset:32000
	ds_read_b64_tr_b16 v[82:83], v74 offset:59392
	ds_read_b64_tr_b16 v[84:85], v74 offset:60160
	s_waitcnt lgkmcnt(0)
	v_mfma_f32_32x32x16_bf16 v[2:17], v[42:45], v[82:85], v[2:17]
	ds_read_b64_tr_b16 v[42:43], v75 offset:35840
	ds_read_b64_tr_b16 v[44:45], v75 offset:37120
	ds_read_b64_tr_b16 v[82:83], v74 offset:62464
	ds_read_b64_tr_b16 v[84:85], v74 offset:63232
	s_waitcnt lgkmcnt(0)
	s_barrier
	v_mfma_f32_32x32x16_bf16 v[2:17], v[42:45], v[82:85], v[2:17]
	s_cbranch_scc1 .LBB0_570
	s_waitcnt vmcnt(21)
	ds_write_b128 v78, v[22:25]
	s_waitcnt vmcnt(20)
	ds_write_b128 v79, v[26:29]
	s_waitcnt vmcnt(19)
	ds_write_b128 v80, v[30:33]
	s_waitcnt vmcnt(18)
	ds_write_b128 v81, v[38:41]
	s_waitcnt vmcnt(17)
	v_lshlrev_b32_e32 v22, 16, v34
	v_and_b32_e32 v23, 0xffff0000, v34
	v_lshlrev_b32_e32 v24, 16, v35
	v_and_b32_e32 v25, 0xffff0000, v35
	v_pk_mul_f32 v[22:23], v[56:57], v[22:23]
	v_pk_mul_f32 v[24:25], v[56:57], v[24:25]
	v_cvt_pk_bf16_f32 v22, v22, v23
	v_cvt_pk_bf16_f32 v23, v24, v25
	v_lshlrev_b32_e32 v24, 16, v36
	v_and_b32_e32 v25, 0xffff0000, v36
	v_lshlrev_b32_e32 v26, 16, v37
	v_and_b32_e32 v27, 0xffff0000, v37
	s_add_u32 s16, s12, s8
	v_pk_mul_f32 v[24:25], v[56:57], v[24:25]
	v_pk_mul_f32 v[26:27], v[56:57], v[26:27]
	s_addc_u32 s17, s13, 0
	v_cvt_pk_bf16_f32 v24, v24, v25
	v_cvt_pk_bf16_f32 v25, v26, v27
	s_or_b32 s14, s14, 31
	ds_write_b128 v77, v[22:25] offset:40960
	s_waitcnt vmcnt(16)
	v_lshlrev_b32_e32 v22, 16, v18
	v_and_b32_e32 v23, 0xffff0000, v18
	s_ashr_i32 s15, s14, 31
	v_readlane_b32 s48, v251, 35
	s_lshl_b64 s[16:17], s[16:17], 10
	v_pk_mul_f32 v[22:23], v[54:55], v[22:23]
	s_lshl_b64 s[14:15], s[14:15], 18
	v_readlane_b32 s58, v251, 45
	v_cvt_pk_bf16_f32 v18, v22, v23
	v_lshlrev_b32_e32 v22, 16, v19
	v_and_b32_e32 v23, 0xffff0000, v19
	v_readlane_b32 s59, v251, 46
	s_add_u32 s11, s58, s14
	v_pk_mul_f32 v[22:23], v[54:55], v[22:23]
	s_addc_u32 s14, s59, s15
	v_cvt_pk_bf16_f32 v19, v22, v23
	v_lshlrev_b32_e32 v22, 16, v20
	v_and_b32_e32 v23, 0xffff0000, v20
	s_add_u32 s11, s11, s16
	v_pk_mul_f32 v[22:23], v[54:55], v[22:23]
	s_addc_u32 s14, s14, s17
	s_lshl_b32 s15, s37, 1
	v_cvt_pk_bf16_f32 v20, v22, v23
	v_lshlrev_b32_e32 v22, 16, v21
	v_and_b32_e32 v23, 0xffff0000, v21
	s_add_u32 s11, s11, s15
	v_pk_mul_f32 v[22:23], v[54:55], v[22:23]
	s_addc_u32 s15, s14, 0
	s_lshl_b32 s14, s36, 1
	v_cvt_pk_bf16_f32 v21, v22, v23
	s_add_u32 s14, s11, s14
	ds_write_b128 v76, v[18:21] offset:40960
	s_addc_u32 s15, s15, 0
	v_lshlrev_b32_e32 v18, 1, v48
	v_mov_b32_e32 v19, v47
	v_lshl_add_u64 v[76:77], s[14:15], 0, v[18:19]
	v_cvt_pk_bf16_f32 v20, v2, s0
	v_lshl_add_u64 v[18:19], v[76:77], 0, v[46:47]
	s_waitcnt lgkmcnt(0)
	s_barrier
	global_store_short v[18:19], v20, off
	v_cvt_pk_bf16_f32 v20, v3, s0
	global_store_short v[18:19], v20, off offset:1024
	v_cvt_pk_bf16_f32 v20, v4, s0
	v_or_b32_e32 v82, 0x2000, v46
	v_mov_b32_e32 v83, v47
	global_store_short v[18:19], v20, off offset:2048
	v_cvt_pk_bf16_f32 v20, v5, s0
	v_or_b32_e32 v84, 0x2400, v46
	v_mov_b32_e32 v85, v47
	global_store_short v[18:19], v20, off offset:3072
	v_cvt_pk_bf16_f32 v20, v6, s0
	v_lshl_add_u64 v[18:19], v[76:77], 0, v[82:83]
	v_or_b32_e32 v86, 0x2800, v46
	v_mov_b32_e32 v87, v47
	global_store_short v[18:19], v20, off
	v_cvt_pk_bf16_f32 v20, v7, s0
	v_lshl_add_u64 v[18:19], v[76:77], 0, v[84:85]
	global_store_short v[18:19], v20, off
	v_cvt_pk_bf16_f32 v20, v8, s0
	v_lshl_add_u64 v[18:19], v[76:77], 0, v[86:87]
	global_store_short v[18:19], v20, off
	v_pk_mul_f32 v[32:33], v[50:51], v[16:17]
	v_pk_mul_f32 v[30:31], v[50:51], v[14:15]
	v_pk_mul_f32 v[28:29], v[50:51], v[12:13]
	v_pk_mul_f32 v[26:27], v[50:51], v[10:11]
	v_pk_mul_f32 v[24:25], v[50:51], v[8:9]
	v_pk_mul_f32 v[22:23], v[50:51], v[6:7]
	v_pk_mul_f32 v[20:21], v[50:51], v[4:5]
	v_pk_mul_f32 v[18:19], v[52:53], v[2:3]
	ds_read_b64_tr_b16 v[2:3], v75
	ds_read_b64_tr_b16 v[4:5], v75 offset:1280
	ds_read_b64_tr_b16 v[34:35], v75 offset:5120
	ds_read_b64_tr_b16 v[36:37], v75 offset:6400
	ds_read_b64_tr_b16 v[38:39], v74 offset:40960
	ds_read_b64_tr_b16 v[40:41], v74 offset:41728
	ds_read_b64_tr_b16 v[50:51], v74 offset:44032
	ds_read_b64_tr_b16 v[52:53], v74 offset:44800
	ds_read_b64_tr_b16 v[54:55], v75 offset:35840
	ds_read_b64_tr_b16 v[56:57], v75 offset:37120
	s_waitcnt lgkmcnt(4)
	v_mfma_f32_32x32x16_bf16 v[18:33], v[2:5], v[38:41], v[18:33]
	v_or_b32_e32 v70, 0x2c00, v46
	v_mov_b32_e32 v71, v47
	v_cvt_pk_bf16_f32 v4, v9, s0
	v_lshl_add_u64 v[2:3], v[76:77], 0, v[70:71]
	global_store_short v[2:3], v4, off
	ds_read_b64_tr_b16 v[2:3], v75 offset:10240
	ds_read_b64_tr_b16 v[4:5], v75 offset:11520
	v_or_b32_e32 v68, 0x4000, v46
	s_waitcnt lgkmcnt(4)
	v_mfma_f32_32x32x16_bf16 v[18:33], v[34:37], v[50:53], v[18:33]
	v_mov_b32_e32 v69, v47
	v_cvt_pk_bf16_f32 v8, v10, s0
	v_lshl_add_u64 v[6:7], v[76:77], 0, v[68:69]
	global_store_short v[6:7], v8, off
	ds_read_b64_tr_b16 v[6:7], v74 offset:47104
	ds_read_b64_tr_b16 v[8:9], v74 offset:47872
	ds_read_b64_tr_b16 v[34:35], v75 offset:15360
	ds_read_b64_tr_b16 v[36:37], v75 offset:16640
	ds_read_b64_tr_b16 v[38:39], v74 offset:50176
	ds_read_b64_tr_b16 v[40:41], v74 offset:50944
	v_or_b32_e32 v66, 0x4400, v46
	v_mov_b32_e32 v67, v47
	s_waitcnt lgkmcnt(4)
	v_mfma_f32_32x32x16_bf16 v[18:33], v[2:5], v[6:9], v[18:33]
	v_cvt_pk_bf16_f32 v4, v11, s0
	v_lshl_add_u64 v[2:3], v[76:77], 0, v[66:67]
	global_store_short v[2:3], v4, off
	ds_read_b64_tr_b16 v[2:3], v75 offset:20480
	ds_read_b64_tr_b16 v[4:5], v75 offset:21760
	v_or_b32_e32 v64, 0x4800, v46
	v_mov_b32_e32 v65, v47
	v_cvt_pk_bf16_f32 v8, v12, s0
	s_waitcnt lgkmcnt(2)
	v_mfma_f32_32x32x16_bf16 v[18:33], v[34:37], v[38:41], v[18:33]
	v_lshl_add_u64 v[6:7], v[76:77], 0, v[64:65]
	global_store_short v[6:7], v8, off
	ds_read_b64_tr_b16 v[6:7], v74 offset:53248
	ds_read_b64_tr_b16 v[8:9], v74 offset:54016
	ds_read_b64_tr_b16 v[34:35], v75 offset:25600
	ds_read_b64_tr_b16 v[36:37], v75 offset:26880
	ds_read_b64_tr_b16 v[38:39], v74 offset:56320
	ds_read_b64_tr_b16 v[40:41], v74 offset:57088
	v_or_b32_e32 v62, 0x4c00, v46
	v_mov_b32_e32 v63, v47
	v_or_b32_e32 v60, 0x6000, v46
	v_mov_b32_e32 v61, v47
	s_waitcnt lgkmcnt(4)
	v_mfma_f32_32x32x16_bf16 v[18:33], v[2:5], v[6:9], v[18:33]
	v_cvt_pk_bf16_f32 v4, v13, s0
	v_lshl_add_u64 v[2:3], v[76:77], 0, v[62:63]
	global_store_short v[2:3], v4, off
	v_cvt_pk_bf16_f32 v8, v14, s0
	v_lshl_add_u64 v[6:7], v[76:77], 0, v[60:61]
	ds_read_b64_tr_b16 v[2:3], v75 offset:30720
	ds_read_b64_tr_b16 v[4:5], v75 offset:32000
	global_store_short v[6:7], v8, off
	s_waitcnt lgkmcnt(2)
	v_mfma_f32_32x32x16_bf16 v[18:33], v[34:37], v[38:41], v[18:33]
	ds_read_b64_tr_b16 v[6:7], v74 offset:59392
	ds_read_b64_tr_b16 v[8:9], v74 offset:60160
	s_ashr_i32 s11, s10, 31
	s_lshl_b64 s[10:11], s[10:11], 8
	s_or_b64 s[10:11], s[10:11], s[8:9]
	ds_read_b64_tr_b16 v[10:11], v74 offset:62464
	ds_read_b64_tr_b16 v[12:13], v74 offset:63232
	s_add_u32 s10, s10, s12
	v_readlane_b32 s49, v251, 36
	s_waitcnt lgkmcnt(2)
	v_mfma_f32_32x32x16_bf16 v[18:33], v[2:5], v[6:9], v[18:33]
	v_readlane_b32 s50, v251, 37
	v_readlane_b32 s51, v251, 38
	v_readlane_b32 s52, v251, 39
	v_readlane_b32 s53, v251, 40
	v_readlane_b32 s54, v251, 41
	v_readlane_b32 s55, v251, 42
	s_addc_u32 s11, s11, s13
	s_lshl_b64 s[10:11], s[10:11], 11
	v_readlane_b32 s40, v253, 0
	v_readlane_b32 s41, v253, 1
	s_add_u32 s8, s40, s10
	s_addc_u32 s10, s41, s11
	s_lshl_b32 s11, s37, 2
	s_waitcnt lgkmcnt(0)
	v_mfma_f32_32x32x16_bf16 v[18:33], v[54:57], v[10:13], v[18:33]
	s_add_u32 s8, s8, s11
	v_or_b32_e32 v44, 0x6800, v46
	v_mov_b32_e32 v45, v47
	s_addc_u32 s11, s10, 0
	s_lshl_b32 s10, s36, 2
	v_or_b32_e32 v42, 0x6c00, v46
	v_mov_b32_e32 v43, v47
	v_cvt_pk_bf16_f32 v4, v16, s0
	v_lshl_add_u64 v[2:3], v[76:77], 0, v[44:45]
	s_add_u32 s10, s8, s10
	v_or_b32_e32 v58, 0x6400, v46
	global_store_short v[2:3], v4, off
	v_cvt_pk_bf16_f32 v4, v17, s0
	v_lshl_add_u64 v[2:3], v[76:77], 0, v[42:43]
	s_addc_u32 s11, s11, 0
	v_lshlrev_b32_e32 v46, 2, v48
	global_store_short v[2:3], v4, off
	v_lshl_add_u64 v[2:3], s[10:11], 0, v[46:47]
	v_lshlrev_b32_e32 v46, 13, v73
	v_lshl_add_u64 v[2:3], v[2:3], 0, v[46:47]
	s_movk_i32 s8, 0x1000
	v_mov_b32_e32 v59, v47
	v_add_co_u32_e32 v4, vcc, s8, v2
	v_cvt_pk_bf16_f32 v34, v15, s0
	v_lshl_add_u64 v[14:15], v[76:77], 0, v[58:59]
	v_addc_co_u32_e32 v5, vcc, 0, v3, vcc
	global_store_short v[14:15], v34, off
	s_barrier
	global_store_dword v[2:3], v18, off
	global_store_dword v[2:3], v19, off offset:2048
	global_store_dword v[4:5], v20, off
	global_store_dword v[4:5], v21, off offset:2048
	v_add_co_u32_e32 v4, vcc, s34, v2
	s_movk_i32 s8, 0x5000
	s_nop 0
	v_addc_co_u32_e32 v5, vcc, 0, v3, vcc
	v_add_co_u32_e32 v6, vcc, s8, v2
	s_mov_b32 s8, 0x8000
	s_nop 0
	v_addc_co_u32_e32 v7, vcc, 0, v3, vcc
	global_store_dword v[6:7], v22, off offset:-4096
	global_store_dword v[4:5], v23, off offset:2048
	global_store_dword v[6:7], v24, off
	global_store_dword v[6:7], v25, off offset:2048
	v_add_co_u32_e32 v4, vcc, s8, v2
	s_mov_b32 s8, 0x9000
	s_nop 0
	v_addc_co_u32_e32 v5, vcc, 0, v3, vcc
	v_add_co_u32_e32 v6, vcc, s8, v2
	s_mov_b32 s8, 0xc000
	s_nop 0
	v_addc_co_u32_e32 v7, vcc, 0, v3, vcc
	global_store_dword v[6:7], v26, off offset:-4096
	global_store_dword v[4:5], v27, off offset:2048
	global_store_dword v[6:7], v28, off
	global_store_dword v[6:7], v29, off offset:2048
	v_add_co_u32_e32 v4, vcc, s8, v2
	s_add_i32 s35, s35, s88
	s_nop 0
	v_addc_co_u32_e32 v5, vcc, 0, v3, vcc
	v_add_co_u32_e32 v2, vcc, 0xd000, v2
	s_add_i32 s24, s24, s25
	s_add_i32 s26, s26, s27
	v_addc_co_u32_e32 v3, vcc, 0, v3, vcc
	s_cmpk_gt_i32 s35, 0xff
	v_readlane_b32 s56, v251, 43
	v_readlane_b32 s57, v251, 44
	v_readlane_b32 s60, v251, 47
	v_readlane_b32 s61, v251, 48
	v_readlane_b32 s62, v251, 49
	v_readlane_b32 s63, v251, 50
	v_readlane_b32 s42, v253, 2
	v_readlane_b32 s43, v253, 3
	v_readlane_b32 s44, v253, 4
	v_readlane_b32 s45, v253, 5
	v_readlane_b32 s46, v253, 6
	v_readlane_b32 s47, v253, 7
	v_readlane_b32 s48, v253, 8
	v_readlane_b32 s49, v253, 9
	v_readlane_b32 s50, v253, 10
	v_readlane_b32 s51, v253, 11
	v_readlane_b32 s52, v253, 12
	v_readlane_b32 s53, v253, 13
	v_readlane_b32 s54, v253, 14
	v_readlane_b32 s55, v253, 15
	global_store_dword v[4:5], v30, off
	global_store_dword v[4:5], v31, off offset:2048
	global_store_dword v[2:3], v32, off
	global_store_dword v[2:3], v33, off offset:2048
	s_cbranch_scc0 .LBB0_569
